# P9 epilogue: last-use residual (T1) loads carry the nt hint
# speedup vs baseline: 1.0044x; 1.0044x over previous
;     __device__ __forceinline__ void piece(size_t row, int col, f32x4 v0, f32x4 v1, const f32x4 a0, const f32x4 a1, const f32x4 b0, const f32x4 b1, const f32x4 c0, const f32x4 c1,
;                                           float mean, float rstd, float& s, float& ss) const {
;     ...
;         if constexpr (RECOMP) { f32x4 r0, r1; unpack8(*(const u32x4*)(Tin + row * DM + col), r0, r1);
;             r0 = (r0 - mean) * rstd * a0 + b0; r1 = (r1 - mean) * rstd * a1 + b1; v0 = r0 * ALPHA + v0; v1 = r1 * ALPHA + v1;
;             if constexpr (MODE == 5) { v0 = v0 + c0; v1 = v1 + c1; } }
;         if constexpr (MODE == 4) { v0 = (v0 - a0 * mean) * rstd + b0; v1 = (v1 - a1 * mean) * rstd + b1;
; #pragma unroll
;             for (int e = 0; e < 4; ++e) { const float x = fmaxf(v0[e], 0.f), y = fmaxf(v1[e], 0.f); v0[e] = x * x; v1[e] = y * y; } }
;         if constexpr (PROD) {
; #pragma unroll
;             for (int e = 0; e < 4; ++e) { s += v0[e] + v1[e]; ss += v0[e] * v0[e] + v1[e] * v1[e]; } }
;         if constexpr (MODE == 5) { float* o = (float*)O + row * ldo + col; *(f32x4*)o = v0; *(f32x4*)(o + 4) = v1; }
;         else *(u32x4*)((bf16_t*)O + row * ldo + col) = pack8(v0, v1);
;     __device__ __forceinline__ void operator()(const f32x4 (&acc)[2][2][4][2], const Unit& u, int wr, int wc, int fr_, int fq_, LAS unsigned char* ldsx) const {
;     ...
;             for (int n = 0; n < 2; ++n) { av[bj][n] = CONS ? *(const f32x4*)(va + colb + bj * HALF + 4 * n) : z; bv[bj][n] = CONS ? *(const f32x4*)(vb + colb + bj * HALF + 4 * n) : z;
;                                           cv[bj][n] = (MODE == 5) ? *(const f32x4*)(bias + colb + bj * HALF + 4 * n) : z; }
; #pragma unroll
;         EPI_FOR_ROWS {
;             const int rl = ai * HALF + wr * 64 + m * 16 + fr; const size_t row = (size_t)u.row0 + rl;
;             float mean = 0.f, rstd = 0.f; if constexpr (CONS) { const f32x2 st = X[rl]; mean = st.x; rstd = st.y; }
;             float s = 0.f, ss = 0.f;
; #pragma unroll
;             for (int bj = 0; bj < 2; ++bj) piece(row, colb + bj * HALF, acc[ai][bj][m][0], acc[ai][bj][m][1], av[bj][0], av[bj][1], bv[bj][0], bv[bj][1], cv[bj][0], cv[bj][1], mean, rstd, s, ss);
;             if constexpr (PROD) { s += __shfl_xor(s, 16); ss += __shfl_xor(ss, 16); s += __shfl_xor(s, 32); ss += __shfl_xor(ss, 32);
.LBB0_1260:
	v_mov_b32_e32 v66, v185
	v_mov_b32_e32 v184, v186
	s_cmp_eq_u32 s34, s20
	v_add_u32_e32 v178, s69, v66
	s_cselect_b32 s1, 0, 0x800
	s_add_i32 s4, s0, s70
	s_ashr_i32 s35, s34, 31
	v_ashrrev_i32_e32 v179, 31, v178
	v_lshl_add_u32 v64, v184, 3, s4
	v_lshl_add_u64 v[180:181], v[178:179], 0, s[34:35]
	v_ashrrev_i32_e32 v65, 31, v64
	v_lshlrev_b64 v[182:183], 11, v[180:181]
	v_lshl_add_u64 v[66:67], s[60:61], 0, v[182:183]
	v_lshlrev_b64 v[176:177], 1, v[64:65]
	v_lshl_add_u64 v[66:67], v[66:67], 0, v[176:177]
	global_load_dwordx4 v[192:195], v[66:67], off nt
	global_load_dwordx4 v[196:199], v[66:67], off offset:256 nt
	v_readlane_b32 s4, v254, 3
	v_lshlrev_b64 v[64:65], 2, v[64:65]
	v_readlane_b32 s5, v254, 4
	v_readlane_b32 s6, v254, 5
	v_readlane_b32 s7, v254, 6
	v_lshl_add_u64 v[68:69], s[4:5], 0, v[64:65]
	s_add_i32 s1, s1, 0
	v_lshl_add_u64 v[80:81], s[6:7], 0, v[64:65]
	global_load_dwordx4 v[72:75], v[80:81], off
	global_load_dwordx4 v[92:95], v[68:69], off
	global_load_dwordx4 v[76:79], v[68:69], off offset:16
	global_load_dwordx4 v[88:91], v[80:81], off offset:16
	global_load_dwordx4 v[64:67], v[80:81], off offset:512
	global_load_dwordx4 v[84:87], v[68:69], off offset:512
	s_nop 0
	global_load_dwordx4 v[68:71], v[68:69], off offset:528
	s_nop 0
	global_load_dwordx4 v[80:83], v[80:81], off offset:528
	v_lshl_add_u32 v179, v178, 3, s1
	v_add_u32_e32 v179, 0x20000, v179
	ds_read_b64 v[200:201], v179
	v_cmp_eq_u32_e32 vcc, 0, v184
	v_readlane_b32 s10, v254, 9
	s_ashr_i32 s0, s0, 6
	s_and_b32 s10, s0, -4
	v_readlane_b32 s11, v254, 10
	s_ashr_i32 s11, s10, 31
	v_readlane_b32 s8, v254, 7
	v_readlane_b32 s9, v254, 8
	v_readlane_b32 s12, v254, 11
	v_readlane_b32 s13, v254, 12
	v_readlane_b32 s14, v254, 13
	v_readlane_b32 s15, v254, 14
	v_readlane_b32 s16, v254, 15
	v_readlane_b32 s17, v254, 16
	v_readlane_b32 s18, v254, 17
	v_readlane_b32 s19, v254, 18
	v_add_u32_e32 v218, 16, v178
	v_ashrrev_i32_e32 v219, 31, v218
	v_lshl_add_u64 v[218:219], v[218:219], 0, s[34:35]
	v_lshlrev_b64 v[218:219], 11, v[218:219]
	v_lshl_add_u64 v[218:219], s[60:61], 0, v[218:219]
	v_lshl_add_u64 v[218:219], v[218:219], 0, v[176:177]
	global_load_dwordx4 v[220:223], v[218:219], off nt
	global_load_dwordx4 v[224:227], v[218:219], off offset:256 nt
	v_add_u32_e32 v218, 32, v178
	v_ashrrev_i32_e32 v219, 31, v218
	v_lshl_add_u64 v[218:219], v[218:219], 0, s[34:35]
	v_lshlrev_b64 v[218:219], 11, v[218:219]
	v_lshl_add_u64 v[218:219], s[60:61], 0, v[218:219]
	v_lshl_add_u64 v[218:219], v[218:219], 0, v[176:177]
	global_load_dwordx4 v[228:231], v[218:219], off nt
	global_load_dwordx4 v[232:235], v[218:219], off offset:256 nt
	v_add_u32_e32 v218, 48, v178
	v_ashrrev_i32_e32 v219, 31, v218
	v_lshl_add_u64 v[218:219], v[218:219], 0, s[34:35]
	v_lshlrev_b64 v[218:219], 11, v[218:219]
	v_lshl_add_u64 v[218:219], s[60:61], 0, v[218:219]
	v_lshl_add_u64 v[218:219], v[218:219], 0, v[176:177]
	global_load_dwordx4 v[236:239], v[218:219], off nt
	global_load_dwordx4 v[240:243], v[218:219], off offset:256 nt
	v_add_u32_e32 v218, 0x80, v178
	v_ashrrev_i32_e32 v219, 31, v218
	v_lshl_add_u64 v[218:219], v[218:219], 0, s[34:35]
	v_lshlrev_b64 v[218:219], 11, v[218:219]
	v_lshl_add_u64 v[218:219], s[60:61], 0, v[218:219]
	v_lshl_add_u64 v[218:219], v[218:219], 0, v[176:177]
	global_load_dwordx4 v[244:247], v[218:219], off nt
	global_load_dwordx4 v[248:251], v[218:219], off offset:256 nt
	s_waitcnt vmcnt(8)
	v_lshlrev_b32_e32 v184, 16, v192
	v_and_b32_e32 v204, 0xffff0000, v192
	v_lshlrev_b32_e32 v192, 16, v193
	v_and_b32_e32 v193, 0xffff0000, v193
	v_lshlrev_b32_e32 v205, 16, v194
	v_and_b32_e32 v206, 0xffff0000, v194
	v_lshlrev_b32_e32 v207, 16, v195
	v_and_b32_e32 v208, 0xffff0000, v195
	v_lshlrev_b32_e32 v209, 16, v196
	v_and_b32_e32 v210, 0xffff0000, v196
	v_lshlrev_b32_e32 v211, 16, v197
	v_and_b32_e32 v212, 0xffff0000, v197
	v_lshlrev_b32_e32 v214, 16, v198
	v_and_b32_e32 v213, 0xffff0000, v198
	v_lshlrev_b32_e32 v215, 16, v199
	v_and_b32_e32 v216, 0xffff0000, v199
	s_waitcnt lgkmcnt(0)
; __device__ __forceinline__ u32x4 pack8(const f32x4 a, const f32x4 b) { u32x4 w; w.x = cvt_pk_bf16(a[0], a[1]); w.y = cvt_pk_bf16(a[2], a[3]); w.z = cvt_pk_bf16(b[0], b[1]); w.w = cvt_pk_bf16(b[2], b[3]); return w; }
; __device__ __forceinline__ void unpack8(const u32x4 w, f32x4& a, f32x4& b) { a = (f32x4){bf_lo(w.x), bf_hi(w.x), bf_lo(w.y), bf_hi(w.y)}; b = (f32x4){bf_lo(w.z), bf_hi(w.z), bf_lo(w.w), bf_hi(w.w)}; }
;     __device__ __forceinline__ void piece(size_t row, int col, f32x4 v0, f32x4 v1, const f32x4 a0, const f32x4 a1, const f32x4 b0, const f32x4 b1, const f32x4 c0, const f32x4 c1,
;                                           float mean, float rstd, float& s, float& ss) const {
;     ...
;         if constexpr (RECOMP) { f32x4 r0, r1; unpack8(*(const u32x4*)(Tin + row * DM + col), r0, r1);
;             r0 = (r0 - mean) * rstd * a0 + b0; r1 = (r1 - mean) * rstd * a1 + b1; v0 = r0 * ALPHA + v0; v1 = r1 * ALPHA + v1;
;             if constexpr (MODE == 5) { v0 = v0 + c0; v1 = v1 + c1; } }
;         if constexpr (MODE == 4) { v0 = (v0 - a0 * mean) * rstd + b0; v1 = (v1 - a1 * mean) * rstd + b1;
; #pragma unroll
;             for (int e = 0; e < 4; ++e) { const float x = fmaxf(v0[e], 0.f), y = fmaxf(v1[e], 0.f); v0[e] = x * x; v1[e] = y * y; } }
;         if constexpr (PROD) {
; #pragma unroll
;             for (int e = 0; e < 4; ++e) { s += v0[e] + v1[e]; ss += v0[e] * v0[e] + v1[e] * v1[e]; } }
;         if constexpr (MODE == 5) { float* o = (float*)O + row * ldo + col; *(f32x4*)o = v0; *(f32x4*)(o + 4) = v1; }
;         else *(u32x4*)((bf16_t*)O + row * ldo + col) = pack8(v0, v1);
;     __device__ __forceinline__ void operator()(const f32x4 (&acc)[2][2][4][2], const Unit& u, int wr, int wc, int fr_, int fq_, LAS unsigned char* ldsx) const {
;     ...
;             if constexpr (PROD) { s += __shfl_xor(s, 16); ss += __shfl_xor(ss, 16); s += __shfl_xor(s, 32); ss += __shfl_xor(ss, 32);
;                 if (fq == 0) st_out[row * 16 + (u.col0 >> 8) * 4 + wc] = (f32x2){s, ss}; }
	v_sub_f32_e32 v193, v193, v200
	v_sub_f32_e32 v192, v192, v200
	v_sub_f32_e32 v195, v204, v200
	v_sub_f32_e32 v194, v184, v200
	v_sub_f32_e32 v197, v208, v200
	v_sub_f32_e32 v196, v207, v200
	v_sub_f32_e32 v199, v206, v200
	v_sub_f32_e32 v198, v205, v200
	v_pk_mul_f32 v[194:195], v[200:201], v[194:195] op_sel:[1,0]
	v_pk_mul_f32 v[192:193], v[200:201], v[192:193] op_sel:[1,0]
	v_pk_mul_f32 v[198:199], v[200:201], v[198:199] op_sel:[1,0]
	v_pk_mul_f32 v[196:197], v[200:201], v[196:197] op_sel:[1,0]
	v_pk_fma_f32 v[192:193], v[94:95], v[192:193], v[74:75]
	v_pk_fma_f32 v[194:195], v[92:93], v[194:195], v[72:73]
	v_pk_fma_f32 v[196:197], v[78:79], v[196:197], v[90:91]
	v_pk_fma_f32 v[198:199], v[76:77], v[198:199], v[88:89]
	v_pk_fma_f32 v[158:159], v[192:193], s[30:31], v[158:159] op_sel_hi:[1,0,1]
	v_pk_fma_f32 v[156:157], v[194:195], s[30:31], v[156:157] op_sel_hi:[1,0,1]
	v_pk_fma_f32 v[192:193], v[196:197], s[30:31], v[154:155] op_sel_hi:[1,0,1]
	v_pk_fma_f32 v[154:155], v[198:199], s[30:31], v[152:153] op_sel_hi:[1,0,1]
	v_sub_f32_e32 v205, v212, v200
	v_sub_f32_e32 v204, v211, v200
	v_sub_f32_e32 v207, v210, v200
	v_sub_f32_e32 v206, v209, v200
	v_sub_f32_e32 v211, v213, v200
	v_pk_add_f32 v[196:197], v[156:157], v[154:155]
	v_sub_f32_e32 v210, v214, v200
	v_pk_mul_f32 v[206:207], v[200:201], v[206:207] op_sel:[1,0]
	v_pk_mul_f32 v[204:205], v[200:201], v[204:205] op_sel:[1,0]
	v_pk_add_f32 v[194:195], v[158:159], v[192:193]
	v_pk_mul_f32 v[198:199], v[192:193], v[192:193]
	v_pk_mul_f32 v[212:213], v[154:155], v[154:155]
	v_cvt_pk_bf16_f32 v154, v154, v155
	v_cvt_pk_bf16_f32 v155, v192, v193
	v_add_f32_e32 v184, 0, v196
	v_pk_mul_f32 v[192:193], v[200:201], v[210:211] op_sel:[1,0]
	v_pk_fma_f32 v[204:205], v[86:87], v[204:205], v[66:67]
	v_pk_fma_f32 v[206:207], v[84:85], v[206:207], v[64:65]
	v_add_f32_e32 v184, v197, v184
	v_pk_fma_f32 v[192:193], v[68:69], v[192:193], v[80:81]
	v_add_f32_e32 v184, v194, v184
	v_pk_fma_f32 v[196:197], v[204:205], s[30:31], v[150:151] op_sel_hi:[1,0,1]
	v_pk_fma_f32 v[150:151], v[206:207], s[30:31], v[148:149] op_sel_hi:[1,0,1]
	v_pk_fma_f32 v[192:193], v[192:193], s[30:31], v[144:145] op_sel_hi:[1,0,1]
	v_sub_f32_e32 v209, v216, v200
	v_sub_f32_e32 v208, v215, v200
	v_add_f32_e32 v184, v195, v184
	v_pk_add_f32 v[144:145], v[150:151], v[192:193]
	v_cvt_pk_bf16_f32 v152, v156, v157
	v_pk_fma_f32 v[156:157], v[156:157], v[156:157], v[212:213]
	v_pk_mul_f32 v[194:195], v[200:201], v[208:209] op_sel:[1,0]
	v_add_f32_e32 v144, v184, v144
	v_cvt_pk_bf16_f32 v153, v158, v159
	v_pk_fma_f32 v[158:159], v[158:159], v[158:159], v[198:199]
	v_pk_fma_f32 v[194:195], v[70:71], v[194:195], v[82:83]
	v_add_f32_e32 v144, v145, v144
	v_add_f32_e32 v145, v157, v156
	v_pk_fma_f32 v[194:195], v[194:195], s[30:31], v[146:147] op_sel_hi:[1,0,1]
	v_pk_mul_f32 v[146:147], v[150:151], v[150:151]
	v_add_f32_e32 v145, v158, v145
	v_pk_fma_f32 v[146:147], v[192:193], v[192:193], v[146:147]
	v_add_f32_e32 v145, v159, v145
	v_add_f32_e32 v148, v145, v146
	v_pk_add_f32 v[146:147], v[146:147], v[148:149] op_sel_hi:[1,0]
	v_mov_b32_e32 v148, v196
	v_mov_b32_e32 v149, v194
	v_mul_f32_e32 v146, v196, v196
	v_pk_fma_f32 v[156:157], v[148:149], v[148:149], v[146:147] op_sel_hi:[1,1,0]
	v_and_b32_e32 v148, 64, v191
	v_xor_b32_e32 v146, 16, v191
	v_add_u32_e32 v149, 64, v148
	v_cmp_lt_i32_e64 s[0:1], v146, v149
	v_mov_b32_e32 v156, v197
	v_pk_mul_f32 v[158:159], v[196:197], v[196:197]
	v_cndmask_b32_e64 v146, v191, v146, s[0:1]
	v_lshlrev_b32_e32 v148, 2, v146
	v_mov_b32_e32 v146, v195
	v_pk_add_f32 v[146:147], v[156:157], v[146:147]
	v_pk_add_f32 v[156:157], v[196:197], v[194:195]
	v_mul_f32_e32 v145, v195, v195
	v_mov_b32_e32 v157, v159
	v_pk_add_f32 v[144:145], v[156:157], v[144:145]
	v_lshl_add_u64 v[156:157], s[88:89], 0, v[182:183]
	v_pk_add_f32 v[144:145], v[144:145], v[146:147]
	ds_bpermute_b32 v146, v148, v144
	ds_bpermute_b32 v147, v148, v145
	v_lshl_add_u64 v[156:157], v[156:157], 0, v[176:177]
	global_store_dwordx4 v[156:157], v[152:155], off
	v_cvt_pk_bf16_f32 v150, v150, v151
	v_cvt_pk_bf16_f32 v151, v196, v197
	s_waitcnt lgkmcnt(0)
	v_pk_add_f32 v[144:145], v[144:145], v[146:147]
	v_xor_b32_e32 v146, 32, v191
	v_cmp_lt_i32_e64 s[0:1], v146, v149
	v_cvt_pk_bf16_f32 v152, v192, v193
	v_cvt_pk_bf16_f32 v153, v194, v195
	global_store_dwordx4 v[156:157], v[150:153], off offset:256
	s_nop 0
	v_cndmask_b32_e64 v146, v191, v146, s[0:1]
	v_lshlrev_b32_e32 v149, 2, v146
	ds_bpermute_b32 v146, v149, v144
	ds_bpermute_b32 v147, v149, v145
	s_and_saveexec_b64 s[0:1], vcc
	s_cbranch_execz .LBB0_1262
	s_waitcnt lgkmcnt(0)
	v_pk_add_f32 v[144:145], v[144:145], v[146:147]
	v_lshlrev_b64 v[146:147], 7, v[180:181]
	v_lshl_add_u64 v[146:147], s[90:91], 0, v[146:147]
	v_lshl_add_u64 v[146:147], s[10:11], 3, v[146:147]
	s_lshl_b32 s22, s68, 3
	v_lshl_add_u64 v[146:147], v[146:147], 0, s[22:23]
	global_store_dwordx2 v[146:147], v[144:145], off
